# GQA attention loop: issue the K(t+3)/V(t+1) LDS-DMA at the start of each step instead of mid-step (more latency tolerance)
# baseline (speedup 1.0000x reference)
; #define WAIT_BAR(N) asm volatile("s_waitcnt vmcnt(" #N ") lgkmcnt(0)\n\ts_barrier":::"memory")
;   #define RESC() do{ if(resc){ asm volatile("s_waitcnt lgkmcnt(0)":::"memory"); \
;       _Pragma("unroll") for(int d_=0;d_<2;++d_) _Pragma("unroll") for(int r=0;r<16;++r)o[d_][r]*=wsf[crow(r,hi)]; } }while(0)
;   #define ROT() do{sl_prev=sl_cur;sl_cur=sl_next;sl_next=(sl_next==(NSLOT-1)*SLOTB)?0:sl_next+SLOTB;}while(0)
;   #define RESC() do{ if(resc){ asm volatile("s_waitcnt lgkmcnt(0)":::"memory"); \
;       _Pragma("unroll") for(int d_=0;d_<4;++d_) _Pragma("unroll") for(int r=0;r<16;++r)o[d_][r]*=wsf[crow(r,hi)]; } }while(0)
;   #define ROT() do{sl_prev=sl_cur;sl_cur=sl_next;sl_next=(sl_next==(NSLOT-1)*SLOTB)?0:sl_next+SLOTB;}while(0)
; template<int THRL> __device__ __forceinline__ void attn_unit(const bf16*Qp,const bf16*__restrict__ Kp,const bf16*__restrict__ Vp,bf16*Op,int opitch,int NT,char*shm,float mfix){
;     ...
;   int t=1;
;     ...
;   for(;t+5<NT;t+=2){
;     STEP(pB0,pB1,pA0,pA1,t,true,true,true);     WAIT_BAR(2); RESC(); ROT();
;     STEP(pA0,pA1,pB0,pB1,t+1,true,true,true);   WAIT_BAR(2); RESC(); ROT();
.LBB0_284:
	s_mov_b32 s7, s20
	s_mov_b32 s20, s17
	v_mov_b64_e32 v[190:191], v[82:83]
	s_mov_b32 s19, s22
	v_mov_b64_e32 v[192:193], v[84:85]
	v_add_u32_e32 v182, s21, v202
	ds_read_b64_tr_b16 v[184:185], v182 offset:24576
	ds_read_b64_tr_b16 v[186:187], v182 offset:25088
	v_lshl_add_u64 v[206:207], v[180:181], 0, s[12:13]
	s_add_i32 s17, s17, s15
	s_mov_b32 s21, m0
	s_mov_b32 m0, s17
	s_nop 0
	global_load_lds_dwordx4 v[206:207], off
	s_mov_b32 m0, s21
	v_lshl_add_u64 v[206:207], v[178:179], 0, s[12:13]
	s_add_i32 s17, s7, s16
	s_mov_b32 s21, m0
	s_mov_b32 m0, s17
	s_nop 0
	global_load_lds_dwordx4 v[206:207], off
	s_mov_b32 m0, s21
	v_add_f32_e32 v82, v66, v67
	v_add_f32_e32 v82, v68, v82
	v_add_f32_e32 v82, v69, v82
	v_add_f32_e32 v82, v70, v82
	v_add_f32_e32 v82, v71, v82
	v_cvt_pk_bf16_f32 v138, v66, v67
	v_cvt_pk_bf16_f32 v139, v68, v69
	s_waitcnt lgkmcnt(9)
	v_mfma_f32_32x32x16_bf16 v[98:113], v[174:177], v[142:145], v[34:49]
	ds_read_b64_tr_b16 v[66:67], v182 offset:28672
	ds_read_b64_tr_b16 v[68:69], v182 offset:29184
	v_add_f32_e32 v82, v72, v82
	v_add_f32_e32 v82, v73, v82
	v_add_f32_e32 v82, v74, v82
	v_add_f32_e32 v114, v75, v82
	s_waitcnt lgkmcnt(9)
	v_mfma_f32_32x32x16_bf16 v[82:97], v[170:173], v[142:145], v[34:49]
	v_cvt_pk_bf16_f32 v140, v70, v71
	v_cvt_pk_bf16_f32 v141, v72, v73
	ds_read_b64_tr_b16 v[70:71], v182 offset:25600
	ds_read_b64_tr_b16 v[72:73], v182 offset:26112
	v_add_f32_e32 v114, v76, v114
	v_add_f32_e32 v114, v77, v114
	v_add_f32_e32 v114, v78, v114
	v_add_f32_e32 v114, v79, v114
	v_cvt_pk_bf16_f32 v134, v74, v75
	v_cvt_pk_bf16_f32 v135, v76, v77
	v_mfma_f32_32x32x16_bf16 v[98:113], v[166:169], v[130:133], v[98:113]
	ds_read_b64_tr_b16 v[74:75], v182 offset:29696
	ds_read_b64_tr_b16 v[76:77], v182 offset:30208
	s_waitcnt lgkmcnt(12)
	v_mfma_f32_32x32x16_bf16 v[82:97], v[162:165], v[130:133], v[82:97]
	v_add_f32_e32 v114, v80, v114
	v_add_f32_e32 v114, v81, v114
	v_add_f32_e32 v114, v50, v114
	v_add_f32_e32 v114, v51, v114
	v_cvt_pk_bf16_f32 v136, v78, v79
	v_cvt_pk_bf16_f32 v137, v80, v81
	ds_read_b64_tr_b16 v[78:79], v182 offset:26624
	ds_read_b64_tr_b16 v[80:81], v182 offset:27136
	v_add_f32_e32 v114, v52, v114
	v_add_f32_e32 v114, v53, v114
	v_add_f32_e32 v114, v54, v114
	v_add_f32_e32 v114, v55, v114
	v_cvt_pk_bf16_f32 v126, v50, v51
	v_cvt_pk_bf16_f32 v127, v52, v53
	s_waitcnt lgkmcnt(13)
	v_mfma_f32_32x32x16_bf16 v[98:113], v[158:161], v[122:125], v[98:113]
	ds_read_b64_tr_b16 v[50:51], v182 offset:30720
	ds_read_b64_tr_b16 v[52:53], v182 offset:31232
	s_waitcnt lgkmcnt(13)
	v_mfma_f32_32x32x16_bf16 v[82:97], v[154:157], v[122:125], v[82:97]
	v_add_f32_e32 v114, v56, v114
	v_add_f32_e32 v114, v57, v114
	v_add_f32_e32 v114, v58, v114
	v_add_f32_e32 v114, v59, v114
	v_cvt_pk_bf16_f32 v128, v54, v55
	v_cvt_pk_bf16_f32 v129, v56, v57
	ds_read_b64_tr_b16 v[54:55], v182 offset:27648
	ds_read_b64_tr_b16 v[56:57], v182 offset:28160
	v_add_f32_e32 v114, v60, v114
	v_add_f32_e32 v114, v61, v114
	v_add_f32_e32 v114, v62, v114
	v_add_f32_e32 v154, v63, v114
	v_cvt_pk_bf16_f32 v114, v58, v59
	v_cvt_pk_bf16_f32 v115, v60, v61
	v_mfma_f32_32x32x16_bf16 v[98:113], v[150:153], v[118:121], v[98:113]
	ds_read_b64_tr_b16 v[58:59], v182 offset:31744
	ds_read_b64_tr_b16 v[60:61], v182 offset:32256
	s_waitcnt lgkmcnt(14)
	v_mfma_f32_32x32x16_bf16 v[82:97], v[146:149], v[118:121], v[82:97]
	v_add_f32_e32 v116, v64, v154
	v_add_f32_e32 v116, v65, v116
	v_add_f32_e32 v182, 0, v116
	v_cvt_pk_bf16_f32 v116, v62, v63
	v_cvt_pk_bf16_f32 v117, v64, v65
	v_mfma_f32_32x32x16_bf16 v[2:17], v[138:141], v[184:187], v[2:17]
	v_exp_f32_e32 v98, v98
	v_exp_f32_e32 v99, v99
	v_exp_f32_e32 v100, v100
	v_exp_f32_e32 v101, v101
	s_waitcnt lgkmcnt(12)
	v_mfma_f32_32x32x16_bf16 v[18:33], v[138:141], v[66:69], v[18:33]
	v_exp_f32_e32 v102, v102
	v_exp_f32_e32 v103, v103
	v_exp_f32_e32 v104, v104
	v_exp_f32_e32 v105, v105
	v_add_u32_e32 v66, s7, v203
	ds_read_b128 v[62:65], v66
	ds_read_b128 v[150:153], v66 offset:4096
	s_waitcnt lgkmcnt(12)
	v_mfma_f32_32x32x16_bf16 v[2:17], v[134:137], v[70:73], v[2:17]
	v_exp_f32_e32 v106, v106
	v_exp_f32_e32 v107, v107
	v_exp_f32_e32 v108, v108
	v_exp_f32_e32 v109, v109
	ds_read_b128 v[154:157], v66 offset:256
	ds_read_b128 v[158:161], v66 offset:4352
	s_waitcnt lgkmcnt(12)
	v_mfma_f32_32x32x16_bf16 v[18:33], v[134:137], v[74:77], v[18:33]
	v_exp_f32_e32 v110, v110
	v_exp_f32_e32 v111, v111
	v_exp_f32_e32 v112, v112
	v_exp_f32_e32 v113, v113
	ds_read_b128 v[162:165], v66 offset:512
	ds_read_b128 v[166:169], v66 offset:4608
	s_waitcnt lgkmcnt(12)
	v_mfma_f32_32x32x16_bf16 v[2:17], v[126:129], v[78:81], v[2:17]
	v_exp_f32_e32 v82, v82
	v_exp_f32_e32 v83, v83
	v_exp_f32_e32 v84, v84
	v_exp_f32_e32 v85, v85
	ds_read_b128 v[170:173], v66 offset:768
	ds_read_b128 v[146:149], v66 offset:4864
	s_waitcnt lgkmcnt(12)
	v_mfma_f32_32x32x16_bf16 v[18:33], v[126:129], v[50:53], v[18:33]
	v_exp_f32_e32 v86, v86
	v_exp_f32_e32 v87, v87
	v_exp_f32_e32 v88, v88
	v_exp_f32_e32 v89, v89
	s_waitcnt lgkmcnt(10)
	v_mfma_f32_32x32x16_bf16 v[2:17], v[114:117], v[54:57], v[2:17]
	v_exp_f32_e32 v90, v90
	v_exp_f32_e32 v91, v91
	v_exp_f32_e32 v92, v92
	v_exp_f32_e32 v93, v93
	s_waitcnt lgkmcnt(8)
	v_mfma_f32_32x32x16_bf16 v[18:33], v[114:117], v[58:61], v[18:33]
	v_exp_f32_e32 v94, v94
	v_exp_f32_e32 v95, v95
	v_exp_f32_e32 v96, v96
	v_exp_f32_e32 v97, v97
	s_waitcnt vmcnt(2) lgkmcnt(0)
	s_barrier
; #define WAIT_BAR(N) asm volatile("s_waitcnt vmcnt(" #N ") lgkmcnt(0)\n\ts_barrier":::"memory")
;   #define RESC() do{ if(resc){ asm volatile("s_waitcnt lgkmcnt(0)":::"memory"); \
;       _Pragma("unroll") for(int d_=0;d_<2;++d_) _Pragma("unroll") for(int r=0;r<16;++r)o[d_][r]*=wsf[crow(r,hi)]; } }while(0)
;   #define ROT() do{sl_prev=sl_cur;sl_cur=sl_next;sl_next=(sl_next==(NSLOT-1)*SLOTB)?0:sl_next+SLOTB;}while(0)
;   #define RESC() do{ if(resc){ asm volatile("s_waitcnt lgkmcnt(0)":::"memory"); \
;       _Pragma("unroll") for(int d_=0;d_<4;++d_) _Pragma("unroll") for(int r=0;r<16;++r)o[d_][r]*=wsf[crow(r,hi)]; } }while(0)
;   #define ROT() do{sl_prev=sl_cur;sl_cur=sl_next;sl_next=(sl_next==(NSLOT-1)*SLOTB)?0:sl_next+SLOTB;}while(0)
; template<int THRL> __device__ __forceinline__ void attn_unit(const bf16*Qp,const bf16*__restrict__ Kp,const bf16*__restrict__ Vp,bf16*Op,int opitch,int NT,char*shm,float mfix){
;     ...
;   int t=1;
;     ...
;   for(;t+5<NT;t+=2){
;     STEP(pB0,pB1,pA0,pA1,t,true,true,true);     WAIT_BAR(2); RESC(); ROT();
;     STEP(pA0,pA1,pB0,pB1,t+1,true,true,true);   WAIT_BAR(2); RESC(); ROT();
;   }
	s_add_i32 s17, s7, 0x2000
	s_cmpk_lg_i32 s7, 0x4000
	s_cselect_b32 s17, s17, 0
	v_add_u32_e32 v183, s20, v202
	ds_read_b64_tr_b16 v[174:175], v183 offset:24576
	ds_read_b64_tr_b16 v[176:177], v183 offset:25088
	s_add_i32 s20, s7, s15
	s_mov_b32 s21, m0
	s_mov_b32 m0, s20
	s_nop 0
	global_load_lds_dwordx4 v[180:181], off
	s_mov_b32 m0, s21
	s_add_i32 s20, s17, s16
	s_mov_b32 s21, m0
	s_mov_b32 m0, s20
	s_nop 0
	global_load_lds_dwordx4 v[178:179], off
	s_mov_b32 m0, s21
	s_waitcnt lgkmcnt(9)
	v_mfma_f32_32x32x16_bf16 v[66:81], v[62:65], v[142:145], v[34:49]
	v_add_f32_e32 v50, v98, v99
	v_add_f32_e32 v50, v100, v50
	v_add_f32_e32 v50, v101, v50
	v_add_f32_e32 v50, v102, v50
	v_add_f32_e32 v50, v103, v50
	v_cvt_pk_bf16_f32 v138, v98, v99
	v_cvt_pk_bf16_f32 v139, v100, v101
	ds_read_b64_tr_b16 v[98:99], v183 offset:28672
	ds_read_b64_tr_b16 v[100:101], v183 offset:29184
	v_add_f32_e32 v50, v104, v50
	v_add_f32_e32 v50, v105, v50
	v_add_f32_e32 v50, v106, v50
	v_add_f32_e32 v114, v107, v50
	s_waitcnt lgkmcnt(10)
	v_mfma_f32_32x32x16_bf16 v[50:65], v[150:153], v[142:145], v[34:49]
	v_cvt_pk_bf16_f32 v140, v102, v103
	v_cvt_pk_bf16_f32 v141, v104, v105
	ds_read_b64_tr_b16 v[102:103], v183 offset:25600
	ds_read_b64_tr_b16 v[104:105], v183 offset:26112
	s_waitcnt lgkmcnt(11)
	v_mfma_f32_32x32x16_bf16 v[66:81], v[154:157], v[130:133], v[66:81]
	v_add_f32_e32 v114, v108, v114
	v_add_f32_e32 v114, v109, v114
	v_add_f32_e32 v114, v110, v114
	v_add_f32_e32 v114, v111, v114
	v_cvt_pk_bf16_f32 v134, v106, v107
	v_cvt_pk_bf16_f32 v135, v108, v109
	ds_read_b64_tr_b16 v[106:107], v183 offset:29696
	ds_read_b64_tr_b16 v[108:109], v183 offset:30208
	s_waitcnt lgkmcnt(12)
	v_mfma_f32_32x32x16_bf16 v[50:65], v[158:161], v[130:133], v[50:65]
	v_add_f32_e32 v114, v112, v114
	v_add_f32_e32 v114, v113, v114
	v_add_f32_e32 v114, v82, v114
	v_add_f32_e32 v114, v83, v114
	v_cvt_pk_bf16_f32 v136, v110, v111
	v_cvt_pk_bf16_f32 v137, v112, v113
	ds_read_b64_tr_b16 v[110:111], v183 offset:26624
	ds_read_b64_tr_b16 v[112:113], v183 offset:27136
	s_waitcnt lgkmcnt(13)
	v_mfma_f32_32x32x16_bf16 v[66:81], v[162:165], v[122:125], v[66:81]
	v_add_f32_e32 v114, v84, v114
	v_add_f32_e32 v114, v85, v114
	v_add_f32_e32 v114, v86, v114
	v_add_f32_e32 v114, v87, v114
	v_cvt_pk_bf16_f32 v126, v82, v83
	v_cvt_pk_bf16_f32 v127, v84, v85
	ds_read_b64_tr_b16 v[82:83], v183 offset:30720
	ds_read_b64_tr_b16 v[84:85], v183 offset:31232
	s_waitcnt lgkmcnt(14)
	v_mfma_f32_32x32x16_bf16 v[50:65], v[166:169], v[122:125], v[50:65]
	v_add_f32_e32 v114, v88, v114
	v_add_f32_e32 v114, v89, v114
	v_add_f32_e32 v114, v90, v114
	v_add_f32_e32 v114, v91, v114
	v_cvt_pk_bf16_f32 v128, v86, v87
	v_cvt_pk_bf16_f32 v129, v88, v89
	ds_read_b64_tr_b16 v[86:87], v183 offset:27648
	ds_read_b64_tr_b16 v[88:89], v183 offset:28160
	s_waitcnt lgkmcnt(14)
	v_mfma_f32_32x32x16_bf16 v[66:81], v[170:173], v[118:121], v[66:81]
	v_add_f32_e32 v114, v92, v114
	v_add_f32_e32 v114, v93, v114
	v_add_f32_e32 v114, v94, v114
	v_add_f32_e32 v150, v95, v114
	v_cvt_pk_bf16_f32 v114, v90, v91
	v_cvt_pk_bf16_f32 v115, v92, v93
	ds_read_b64_tr_b16 v[90:91], v183 offset:31744
	ds_read_b64_tr_b16 v[92:93], v183 offset:32256
	v_mfma_f32_32x32x16_bf16 v[50:65], v[146:149], v[118:121], v[50:65]
	v_add_f32_e32 v116, v96, v150
	v_add_f32_e32 v116, v97, v116
	v_add_f32_e32 v183, 0, v116
	v_cvt_pk_bf16_f32 v116, v94, v95
	v_cvt_pk_bf16_f32 v117, v96, v97
	s_add_i32 s18, s18, 2
	s_waitcnt lgkmcnt(14)
	v_mfma_f32_32x32x16_bf16 v[2:17], v[138:141], v[174:177], v[2:17]
	v_exp_f32_e32 v66, v66
	v_exp_f32_e32 v67, v67
	v_exp_f32_e32 v68, v68
	v_exp_f32_e32 v69, v69
	s_waitcnt lgkmcnt(12)
	v_mfma_f32_32x32x16_bf16 v[18:33], v[138:141], v[98:101], v[18:33]
	v_exp_f32_e32 v70, v70
	v_exp_f32_e32 v71, v71
	v_exp_f32_e32 v72, v72
	v_exp_f32_e32 v73, v73
	v_add_u32_e32 v94, s17, v203
	ds_read_b128 v[174:177], v94
	ds_read_b128 v[170:173], v94 offset:4096
	s_waitcnt lgkmcnt(12)
	v_mfma_f32_32x32x16_bf16 v[2:17], v[134:137], v[102:105], v[2:17]
	v_exp_f32_e32 v74, v74
	v_exp_f32_e32 v75, v75
	v_exp_f32_e32 v76, v76
	v_exp_f32_e32 v77, v77
	ds_read_b128 v[166:169], v94 offset:256
	ds_read_b128 v[162:165], v94 offset:4352
	s_waitcnt lgkmcnt(12)
	v_mfma_f32_32x32x16_bf16 v[18:33], v[134:137], v[106:109], v[18:33]
	v_exp_f32_e32 v78, v78
	v_exp_f32_e32 v79, v79
	v_exp_f32_e32 v80, v80
	v_exp_f32_e32 v81, v81
	ds_read_b128 v[158:161], v94 offset:512
	ds_read_b128 v[154:157], v94 offset:4608
	s_waitcnt lgkmcnt(12)
	v_mfma_f32_32x32x16_bf16 v[2:17], v[126:129], v[110:113], v[2:17]
	v_exp_f32_e32 v50, v50
	v_exp_f32_e32 v51, v51
	v_exp_f32_e32 v52, v52
	v_exp_f32_e32 v53, v53
	ds_read_b128 v[150:153], v94 offset:768
	ds_read_b128 v[146:149], v94 offset:4864
	s_waitcnt lgkmcnt(12)
	v_mfma_f32_32x32x16_bf16 v[18:33], v[126:129], v[82:85], v[18:33]
	v_exp_f32_e32 v54, v54
	v_exp_f32_e32 v55, v55
	v_exp_f32_e32 v56, v56
	v_exp_f32_e32 v57, v57
	s_waitcnt lgkmcnt(10)
	v_mfma_f32_32x32x16_bf16 v[2:17], v[114:117], v[86:89], v[2:17]
	v_exp_f32_e32 v58, v58
	v_exp_f32_e32 v59, v59
	v_exp_f32_e32 v60, v60
	v_exp_f32_e32 v61, v61
	s_waitcnt lgkmcnt(8)
	v_mfma_f32_32x32x16_bf16 v[18:33], v[114:117], v[90:93], v[18:33]
	v_exp_f32_e32 v62, v62
	v_exp_f32_e32 v63, v63
	v_exp_f32_e32 v64, v64
	v_exp_f32_e32 v65, v65
	s_add_i32 s20, s17, 0x2000
	s_waitcnt vmcnt(2) lgkmcnt(0)
	s_barrier
	s_cmpk_lg_i32 s17, 0x4000
	v_add_f32_e32 v86, v199, v182
	s_cselect_b32 s20, s20, 0
	s_add_i32 s22, s22, 2
	v_lshl_add_u64 v[178:179], v[178:179], 0, s[38:39]
	v_lshl_add_u64 v[180:181], v[180:181], 0, s[38:39]
	v_lshl_add_u64 v[82:83], v[190:191], 0, s[38:39]
	v_lshl_add_u64 v[84:85], v[192:193], 0, s[38:39]
	s_mov_b32 s21, s7
	s_cmp_ge_u32 s18, s6
	v_add_f32_e32 v199, v86, v183
	s_cbranch_scc0 .LBB0_284
	s_add_i32 s6, s18, 1
	s_cmp_ge_u32 s6, s90
	s_cbranch_scc1 .LBB0_319
	s_add_i32 s21, s90, -2

; #define WAIT_BAR(N) asm volatile("s_waitcnt vmcnt(" #N ") lgkmcnt(0)\n\ts_barrier":::"memory")
;   #define RESC() do{ if(resc){ asm volatile("s_waitcnt lgkmcnt(0)":::"memory"); \
;       _Pragma("unroll") for(int d_=0;d_<2;++d_) _Pragma("unroll") for(int r=0;r<16;++r)o[d_][r]*=wsf[crow(r,hi)]; } }while(0)
;   #define ROT() do{sl_prev=sl_cur;sl_cur=sl_next;sl_next=(sl_next==(NSLOT-1)*SLOTB)?0:sl_next+SLOTB;}while(0)
;   #define RESC() do{ if(resc){ asm volatile("s_waitcnt lgkmcnt(0)":::"memory"); \
;       _Pragma("unroll") for(int d_=0;d_<4;++d_) _Pragma("unroll") for(int r=0;r<16;++r)o[d_][r]*=wsf[crow(r,hi)]; } }while(0)
;   #define ROT() do{sl_prev=sl_cur;sl_cur=sl_next;sl_next=(sl_next==(NSLOT-1)*SLOTB)?0:sl_next+SLOTB;}while(0)
; template<int THRL> __device__ __forceinline__ void attn_unit(const bf16*Qp,const bf16*__restrict__ Kp,const bf16*__restrict__ Vp,bf16*Op,int opitch,int NT,char*shm,float mfix){
;     ...
;   int t=1;
;     ...
;   for(;t+5<NT;t+=2){
;     STEP(pB0,pB1,pA0,pA1,t,true,true,true);     WAIT_BAR(2); RESC(); ROT();
;     STEP(pA0,pA1,pB0,pB1,t+1,true,true,true);   WAIT_BAR(2); RESC(); ROT();
.LBB0_837:
	s_mov_b32 s7, s62
	s_mov_b32 s62, s31
	v_mov_b64_e32 v[190:191], v[84:85]
	s_mov_b32 s61, s74
	v_mov_b64_e32 v[192:193], v[82:83]
	v_add_u32_e32 v182, s63, v202
	ds_read_b64_tr_b16 v[184:185], v182 offset:24576
	ds_read_b64_tr_b16 v[186:187], v182 offset:25088
	v_lshl_add_u64 v[206:207], v[180:181], 0, s[20:21]
	s_add_i32 s31, s31, s15
	s_mov_b32 s63, m0
	s_mov_b32 m0, s31
	s_nop 0
	global_load_lds_dwordx4 v[206:207], off
	s_mov_b32 m0, s63
	v_lshl_add_u64 v[206:207], v[178:179], 0, s[20:21]
	s_add_i32 s31, s7, s30
	s_mov_b32 s63, m0
	s_mov_b32 m0, s31
	s_nop 0
	global_load_lds_dwordx4 v[206:207], off
	s_mov_b32 m0, s63
	v_add_f32_e32 v82, v66, v67
	v_add_f32_e32 v82, v68, v82
	v_add_f32_e32 v82, v69, v82
	v_add_f32_e32 v82, v70, v82
	v_add_f32_e32 v82, v71, v82
	v_cvt_pk_bf16_f32 v142, v66, v67
	v_cvt_pk_bf16_f32 v143, v68, v69
	s_waitcnt lgkmcnt(9)
	v_mfma_f32_32x32x16_bf16 v[98:113], v[174:177], v[138:141], v[34:49]
	ds_read_b64_tr_b16 v[66:67], v182 offset:28672
	ds_read_b64_tr_b16 v[68:69], v182 offset:29184
	v_add_f32_e32 v82, v72, v82
	v_add_f32_e32 v82, v73, v82
	v_add_f32_e32 v82, v74, v82
	v_add_f32_e32 v114, v75, v82
	s_waitcnt lgkmcnt(9)
	v_mfma_f32_32x32x16_bf16 v[82:97], v[170:173], v[138:141], v[34:49]
	v_cvt_pk_bf16_f32 v144, v70, v71
	v_cvt_pk_bf16_f32 v145, v72, v73
	ds_read_b64_tr_b16 v[70:71], v182 offset:25600
	ds_read_b64_tr_b16 v[72:73], v182 offset:26112
	v_add_f32_e32 v114, v76, v114
	v_add_f32_e32 v114, v77, v114
	v_add_f32_e32 v114, v78, v114
	v_add_f32_e32 v114, v79, v114
	v_cvt_pk_bf16_f32 v134, v74, v75
	v_cvt_pk_bf16_f32 v135, v76, v77
	v_mfma_f32_32x32x16_bf16 v[98:113], v[166:169], v[130:133], v[98:113]
	ds_read_b64_tr_b16 v[74:75], v182 offset:29696
	ds_read_b64_tr_b16 v[76:77], v182 offset:30208
	s_waitcnt lgkmcnt(12)
	v_mfma_f32_32x32x16_bf16 v[82:97], v[162:165], v[130:133], v[82:97]
	v_add_f32_e32 v114, v80, v114
	v_add_f32_e32 v114, v81, v114
	v_add_f32_e32 v114, v50, v114
	v_add_f32_e32 v114, v51, v114
	v_cvt_pk_bf16_f32 v136, v78, v79
	v_cvt_pk_bf16_f32 v137, v80, v81
	ds_read_b64_tr_b16 v[78:79], v182 offset:26624
	ds_read_b64_tr_b16 v[80:81], v182 offset:27136
	v_add_f32_e32 v114, v52, v114
	v_add_f32_e32 v114, v53, v114
	v_add_f32_e32 v114, v54, v114
	v_add_f32_e32 v114, v55, v114
	v_cvt_pk_bf16_f32 v126, v50, v51
	v_cvt_pk_bf16_f32 v127, v52, v53
	s_waitcnt lgkmcnt(13)
	v_mfma_f32_32x32x16_bf16 v[98:113], v[158:161], v[122:125], v[98:113]
	ds_read_b64_tr_b16 v[50:51], v182 offset:30720
	ds_read_b64_tr_b16 v[52:53], v182 offset:31232
	s_waitcnt lgkmcnt(13)
	v_mfma_f32_32x32x16_bf16 v[82:97], v[154:157], v[122:125], v[82:97]
	v_add_f32_e32 v114, v56, v114
	v_add_f32_e32 v114, v57, v114
	v_add_f32_e32 v114, v58, v114
	v_add_f32_e32 v114, v59, v114
	v_cvt_pk_bf16_f32 v128, v54, v55
	v_cvt_pk_bf16_f32 v129, v56, v57
	ds_read_b64_tr_b16 v[54:55], v182 offset:27648
	ds_read_b64_tr_b16 v[56:57], v182 offset:28160
	v_add_f32_e32 v114, v60, v114
	v_add_f32_e32 v114, v61, v114
	v_add_f32_e32 v114, v62, v114
	v_add_f32_e32 v154, v63, v114
	v_cvt_pk_bf16_f32 v114, v58, v59
	v_cvt_pk_bf16_f32 v115, v60, v61
	v_mfma_f32_32x32x16_bf16 v[98:113], v[150:153], v[118:121], v[98:113]
	ds_read_b64_tr_b16 v[58:59], v182 offset:31744
	ds_read_b64_tr_b16 v[60:61], v182 offset:32256
	s_waitcnt lgkmcnt(14)
	v_mfma_f32_32x32x16_bf16 v[82:97], v[146:149], v[118:121], v[82:97]
	v_add_f32_e32 v116, v64, v154
	v_add_f32_e32 v116, v65, v116
	v_add_f32_e32 v182, 0, v116
	v_cvt_pk_bf16_f32 v116, v62, v63
	v_cvt_pk_bf16_f32 v117, v64, v65
	v_mfma_f32_32x32x16_bf16 v[2:17], v[142:145], v[184:187], v[2:17]
	v_exp_f32_e32 v98, v98
	v_exp_f32_e32 v99, v99
	v_exp_f32_e32 v100, v100
	v_exp_f32_e32 v101, v101
	s_waitcnt lgkmcnt(12)
	v_mfma_f32_32x32x16_bf16 v[18:33], v[142:145], v[66:69], v[18:33]
	v_exp_f32_e32 v102, v102
	v_exp_f32_e32 v103, v103
	v_exp_f32_e32 v104, v104
	v_exp_f32_e32 v105, v105
	v_add_u32_e32 v66, s7, v203
	ds_read_b128 v[62:65], v66
	ds_read_b128 v[146:149], v66 offset:4096
	s_waitcnt lgkmcnt(12)
	v_mfma_f32_32x32x16_bf16 v[2:17], v[134:137], v[70:73], v[2:17]
	v_exp_f32_e32 v106, v106
	v_exp_f32_e32 v107, v107
	v_exp_f32_e32 v108, v108
	v_exp_f32_e32 v109, v109
	ds_read_b128 v[150:153], v66 offset:256
	ds_read_b128 v[154:157], v66 offset:4352
	s_waitcnt lgkmcnt(12)
	v_mfma_f32_32x32x16_bf16 v[18:33], v[134:137], v[74:77], v[18:33]
	v_exp_f32_e32 v110, v110
	v_exp_f32_e32 v111, v111
	v_exp_f32_e32 v112, v112
	v_exp_f32_e32 v113, v113
	ds_read_b128 v[158:161], v66 offset:512
	ds_read_b128 v[162:165], v66 offset:4608
	s_waitcnt lgkmcnt(12)
	v_mfma_f32_32x32x16_bf16 v[2:17], v[126:129], v[78:81], v[2:17]
	v_exp_f32_e32 v82, v82
	v_exp_f32_e32 v83, v83
	v_exp_f32_e32 v84, v84
	v_exp_f32_e32 v85, v85
	ds_read_b128 v[166:169], v66 offset:768
	ds_read_b128 v[170:173], v66 offset:4864
	s_waitcnt lgkmcnt(12)
	v_mfma_f32_32x32x16_bf16 v[18:33], v[126:129], v[50:53], v[18:33]
	v_exp_f32_e32 v86, v86
	v_exp_f32_e32 v87, v87
	v_exp_f32_e32 v88, v88
	v_exp_f32_e32 v89, v89
	s_waitcnt lgkmcnt(10)
	v_mfma_f32_32x32x16_bf16 v[2:17], v[114:117], v[54:57], v[2:17]
	v_exp_f32_e32 v90, v90
	v_exp_f32_e32 v91, v91
	v_exp_f32_e32 v92, v92
	v_exp_f32_e32 v93, v93
	s_waitcnt lgkmcnt(8)
	v_mfma_f32_32x32x16_bf16 v[18:33], v[114:117], v[58:61], v[18:33]
	v_exp_f32_e32 v94, v94
	v_exp_f32_e32 v95, v95
	v_exp_f32_e32 v96, v96
	v_exp_f32_e32 v97, v97
	s_waitcnt vmcnt(2) lgkmcnt(0)
	s_barrier
; #define WAIT_BAR(N) asm volatile("s_waitcnt vmcnt(" #N ") lgkmcnt(0)\n\ts_barrier":::"memory")
;   #define RESC() do{ if(resc){ asm volatile("s_waitcnt lgkmcnt(0)":::"memory"); \
;       _Pragma("unroll") for(int d_=0;d_<2;++d_) _Pragma("unroll") for(int r=0;r<16;++r)o[d_][r]*=wsf[crow(r,hi)]; } }while(0)
;   #define ROT() do{sl_prev=sl_cur;sl_cur=sl_next;sl_next=(sl_next==(NSLOT-1)*SLOTB)?0:sl_next+SLOTB;}while(0)
;   #define RESC() do{ if(resc){ asm volatile("s_waitcnt lgkmcnt(0)":::"memory"); \
;       _Pragma("unroll") for(int d_=0;d_<4;++d_) _Pragma("unroll") for(int r=0;r<16;++r)o[d_][r]*=wsf[crow(r,hi)]; } }while(0)
;   #define ROT() do{sl_prev=sl_cur;sl_cur=sl_next;sl_next=(sl_next==(NSLOT-1)*SLOTB)?0:sl_next+SLOTB;}while(0)
; template<int THRL> __device__ __forceinline__ void attn_unit(const bf16*Qp,const bf16*__restrict__ Kp,const bf16*__restrict__ Vp,bf16*Op,int opitch,int NT,char*shm,float mfix){
;     ...
;   int t=1;
;     ...
;   for(;t+5<NT;t+=2){
;     STEP(pB0,pB1,pA0,pA1,t,true,true,true);     WAIT_BAR(2); RESC(); ROT();
;     STEP(pA0,pA1,pB0,pB1,t+1,true,true,true);   WAIT_BAR(2); RESC(); ROT();
;   }
	s_add_i32 s31, s7, 0x2000
	s_cmpk_lg_i32 s7, 0x4000
	s_cselect_b32 s31, s31, 0
	v_add_u32_e32 v183, s62, v202
	ds_read_b64_tr_b16 v[174:175], v183 offset:24576
	ds_read_b64_tr_b16 v[176:177], v183 offset:25088
	s_add_i32 s62, s7, s15
	s_mov_b32 s63, m0
	s_mov_b32 m0, s62
	s_nop 0
	global_load_lds_dwordx4 v[180:181], off
	s_mov_b32 m0, s63
	s_add_i32 s62, s31, s30
	s_mov_b32 s63, m0
	s_mov_b32 m0, s62
	s_nop 0
	global_load_lds_dwordx4 v[178:179], off
	s_mov_b32 m0, s63
	s_waitcnt lgkmcnt(9)
	v_mfma_f32_32x32x16_bf16 v[66:81], v[62:65], v[138:141], v[34:49]
	v_add_f32_e32 v50, v98, v99
	v_add_f32_e32 v50, v100, v50
	v_add_f32_e32 v50, v101, v50
	v_add_f32_e32 v50, v102, v50
	v_add_f32_e32 v50, v103, v50
	v_cvt_pk_bf16_f32 v142, v98, v99
	v_cvt_pk_bf16_f32 v143, v100, v101
	ds_read_b64_tr_b16 v[98:99], v183 offset:28672
	ds_read_b64_tr_b16 v[100:101], v183 offset:29184
	v_add_f32_e32 v50, v104, v50
	v_add_f32_e32 v50, v105, v50
	v_add_f32_e32 v50, v106, v50
	v_add_f32_e32 v114, v107, v50
	s_waitcnt lgkmcnt(10)
	v_mfma_f32_32x32x16_bf16 v[50:65], v[146:149], v[138:141], v[34:49]
	v_cvt_pk_bf16_f32 v144, v102, v103
	v_cvt_pk_bf16_f32 v145, v104, v105
	ds_read_b64_tr_b16 v[102:103], v183 offset:25600
	ds_read_b64_tr_b16 v[104:105], v183 offset:26112
	s_waitcnt lgkmcnt(11)
	v_mfma_f32_32x32x16_bf16 v[66:81], v[150:153], v[130:133], v[66:81]
	v_add_f32_e32 v114, v108, v114
	v_add_f32_e32 v114, v109, v114
	v_add_f32_e32 v114, v110, v114
	v_add_f32_e32 v114, v111, v114
	v_cvt_pk_bf16_f32 v134, v106, v107
	v_cvt_pk_bf16_f32 v135, v108, v109
	ds_read_b64_tr_b16 v[106:107], v183 offset:29696
	ds_read_b64_tr_b16 v[108:109], v183 offset:30208
	s_waitcnt lgkmcnt(12)
	v_mfma_f32_32x32x16_bf16 v[50:65], v[154:157], v[130:133], v[50:65]
	v_add_f32_e32 v114, v112, v114
	v_add_f32_e32 v114, v113, v114
	v_add_f32_e32 v114, v82, v114
	v_add_f32_e32 v114, v83, v114
	v_cvt_pk_bf16_f32 v136, v110, v111
	v_cvt_pk_bf16_f32 v137, v112, v113
	ds_read_b64_tr_b16 v[110:111], v183 offset:26624
	ds_read_b64_tr_b16 v[112:113], v183 offset:27136
	s_waitcnt lgkmcnt(13)
	v_mfma_f32_32x32x16_bf16 v[66:81], v[158:161], v[122:125], v[66:81]
	v_add_f32_e32 v114, v84, v114
	v_add_f32_e32 v114, v85, v114
	v_add_f32_e32 v114, v86, v114
	v_add_f32_e32 v114, v87, v114
	v_cvt_pk_bf16_f32 v126, v82, v83
	v_cvt_pk_bf16_f32 v127, v84, v85
	ds_read_b64_tr_b16 v[82:83], v183 offset:30720
	ds_read_b64_tr_b16 v[84:85], v183 offset:31232
	s_waitcnt lgkmcnt(14)
	v_mfma_f32_32x32x16_bf16 v[50:65], v[162:165], v[122:125], v[50:65]
	v_add_f32_e32 v114, v88, v114
	v_add_f32_e32 v114, v89, v114
	v_add_f32_e32 v114, v90, v114
	v_add_f32_e32 v114, v91, v114
	v_cvt_pk_bf16_f32 v128, v86, v87
	v_cvt_pk_bf16_f32 v129, v88, v89
	ds_read_b64_tr_b16 v[86:87], v183 offset:27648
	ds_read_b64_tr_b16 v[88:89], v183 offset:28160
	s_waitcnt lgkmcnt(14)
	v_mfma_f32_32x32x16_bf16 v[66:81], v[166:169], v[118:121], v[66:81]
	v_add_f32_e32 v114, v92, v114
	v_add_f32_e32 v114, v93, v114
	v_add_f32_e32 v114, v94, v114
	v_add_f32_e32 v146, v95, v114
	v_cvt_pk_bf16_f32 v114, v90, v91
	v_cvt_pk_bf16_f32 v115, v92, v93
	ds_read_b64_tr_b16 v[90:91], v183 offset:31744
	ds_read_b64_tr_b16 v[92:93], v183 offset:32256
	v_mfma_f32_32x32x16_bf16 v[50:65], v[170:173], v[118:121], v[50:65]
	v_add_f32_e32 v116, v96, v146
	v_add_f32_e32 v116, v97, v116
	v_add_f32_e32 v183, 0, v116
	v_cvt_pk_bf16_f32 v116, v94, v95
	v_cvt_pk_bf16_f32 v117, v96, v97
	s_add_i32 s60, s60, 2
	s_waitcnt lgkmcnt(14)
	v_mfma_f32_32x32x16_bf16 v[2:17], v[142:145], v[174:177], v[2:17]
	v_exp_f32_e32 v66, v66
	v_exp_f32_e32 v67, v67
	v_exp_f32_e32 v68, v68
	v_exp_f32_e32 v69, v69
	s_waitcnt lgkmcnt(12)
	v_mfma_f32_32x32x16_bf16 v[18:33], v[142:145], v[98:101], v[18:33]
	v_exp_f32_e32 v70, v70
	v_exp_f32_e32 v71, v71
	v_exp_f32_e32 v72, v72
	v_exp_f32_e32 v73, v73
	v_add_u32_e32 v94, s31, v203
	ds_read_b128 v[174:177], v94
	ds_read_b128 v[170:173], v94 offset:4096
	s_waitcnt lgkmcnt(12)
	v_mfma_f32_32x32x16_bf16 v[2:17], v[134:137], v[102:105], v[2:17]
	v_exp_f32_e32 v74, v74
	v_exp_f32_e32 v75, v75
	v_exp_f32_e32 v76, v76
	v_exp_f32_e32 v77, v77
	ds_read_b128 v[166:169], v94 offset:256
	ds_read_b128 v[162:165], v94 offset:4352
	s_waitcnt lgkmcnt(12)
	v_mfma_f32_32x32x16_bf16 v[18:33], v[134:137], v[106:109], v[18:33]
	v_exp_f32_e32 v78, v78
	v_exp_f32_e32 v79, v79
	v_exp_f32_e32 v80, v80
	v_exp_f32_e32 v81, v81
	ds_read_b128 v[158:161], v94 offset:512
	ds_read_b128 v[154:157], v94 offset:4608
	s_waitcnt lgkmcnt(12)
	v_mfma_f32_32x32x16_bf16 v[2:17], v[126:129], v[110:113], v[2:17]
	v_exp_f32_e32 v50, v50
	v_exp_f32_e32 v51, v51
	v_exp_f32_e32 v52, v52
	v_exp_f32_e32 v53, v53
	ds_read_b128 v[150:153], v94 offset:768
	ds_read_b128 v[146:149], v94 offset:4864
	s_waitcnt lgkmcnt(12)
	v_mfma_f32_32x32x16_bf16 v[18:33], v[126:129], v[82:85], v[18:33]
	v_exp_f32_e32 v54, v54
	v_exp_f32_e32 v55, v55
	v_exp_f32_e32 v56, v56
	v_exp_f32_e32 v57, v57
	s_waitcnt lgkmcnt(10)
	v_mfma_f32_32x32x16_bf16 v[2:17], v[114:117], v[86:89], v[2:17]
	v_exp_f32_e32 v58, v58
	v_exp_f32_e32 v59, v59
	v_exp_f32_e32 v60, v60
	v_exp_f32_e32 v61, v61
	s_waitcnt lgkmcnt(8)
	v_mfma_f32_32x32x16_bf16 v[18:33], v[114:117], v[90:93], v[18:33]
	v_exp_f32_e32 v62, v62
	v_exp_f32_e32 v63, v63
	v_exp_f32_e32 v64, v64
	v_exp_f32_e32 v65, v65
	s_add_i32 s62, s31, 0x2000
	s_waitcnt vmcnt(2) lgkmcnt(0)
	s_barrier
	s_cmpk_lg_i32 s31, 0x4000
	v_add_f32_e32 v86, v199, v182
	s_cselect_b32 s62, s62, 0
	s_add_i32 s74, s74, 2
	v_lshl_add_u64 v[178:179], v[178:179], 0, s[22:23]
	v_lshl_add_u64 v[180:181], v[180:181], 0, s[22:23]
	v_lshl_add_u64 v[84:85], v[190:191], 0, s[22:23]
	v_lshl_add_u64 v[82:83], v[192:193], 0, s[22:23]
	s_mov_b32 s63, s7
	s_cmp_ge_u32 s60, s6
	v_add_f32_e32 v199, v86, v183
	s_cbranch_scc0 .LBB0_837
	s_add_i32 s6, s60, 1
	s_cmp_ge_u32 s6, s84
	s_cbranch_scc1 .LBB0_872
	s_add_i32 s63, s84, -2
